# ew_init processes 4 rows per iteration (16 loads in flight) on top of attention prefetch, pool batching and attention unit remap
# baseline (speedup 1.0000x reference)
; __device__ __forceinline__ void ew_init(const float* x, const float* gain, bf16* H, int gw, int ngw, int lane) {
;     f32x4 g[4];
; #pragma unroll
;     for (int j = 0; j < 4; ++j) g[j] = *((const f32x4*)gain + lane + 64 * j);
;     for (int m = gw; m < NTOK; m += ngw) {
;         const f32x4* xr = (const f32x4*)(x + (size_t)m * DM) + lane; f32x4 v[4]; float s = 0.f;
; #pragma unroll
;         for (int j = 0; j < 4; ++j) { v[j] = __builtin_nontemporal_load(xr + 64 * j); s += (v[j].x * v[j].x + v[j].y * v[j].y) + (v[j].z * v[j].z + v[j].w * v[j].w); }
;         const float rstd = rsqrtf(wave_sum(s) * (1.f / DM) + RMS_EPS);
.LBB0_194:
.LBB0_195:
	s_cmpk_gt_i32 s96, 0x7fff
	s_cbranch_scc1 .LBB0_199
	v_readlane_b32 s56, v253, 30
	v_lshlrev_b32_e32 v178, 4, v184
	v_readlane_b32 s62, v253, 36
	v_readlane_b32 s63, v253, 37
	s_nop 4
	global_load_dwordx4 v[0:3], v178, s[62:63] offset:3072
	global_load_dwordx4 v[4:7], v178, s[62:63] offset:2048
	global_load_dwordx4 v[8:11], v178, s[62:63] offset:1024
	global_load_dwordx4 v[12:15], v178, s[62:63]
	v_and_b32_e32 v16, 64, v226
	v_add_u32_e32 v16, 64, v16
	v_xor_b32_e32 v17, 1, v226
	v_cmp_lt_i32_e32 vcc, v17, v16
	s_mov_b32 s6, s97
	v_readlane_b32 s70, v253, 44
	v_cndmask_b32_e32 v17, v226, v17, vcc
	v_lshlrev_b32_e32 v20, 2, v17
	v_xor_b32_e32 v17, 2, v226
	v_cmp_lt_i32_e32 vcc, v17, v16
	v_readlane_b32 s71, v253, 45
	s_ashr_i32 s97, s96, 31
	v_cndmask_b32_e32 v17, v226, v17, vcc
	v_lshlrev_b32_e32 v21, 2, v17
	v_xor_b32_e32 v17, 4, v226
	v_cmp_lt_i32_e32 vcc, v17, v16
	v_readlane_b32 s70, v254, 57
	s_lshl_b64 s[4:5], s[96:97], 11
	v_cndmask_b32_e32 v17, v226, v17, vcc
	v_lshlrev_b32_e32 v22, 2, v17
	v_xor_b32_e32 v17, 8, v226
	v_cmp_lt_i32_e32 vcc, v17, v16
	v_readlane_b32 s71, v254, 58
	s_add_u32 s4, s70, s4
	v_cndmask_b32_e32 v17, v226, v17, vcc
	v_lshlrev_b32_e32 v23, 2, v17
	v_xor_b32_e32 v17, 16, v226
	v_cmp_lt_i32_e32 vcc, v17, v16
	s_addc_u32 s5, s71, s5
	v_readlane_b32 s7, v254, 24
	v_cndmask_b32_e32 v17, v226, v17, vcc
	v_lshlrev_b32_e32 v24, 2, v17
	v_xor_b32_e32 v17, 32, v226
	v_cmp_lt_i32_e32 vcc, v17, v16
	v_readlane_b32 s66, v253, 40
	v_readlane_b32 s67, v253, 41
	v_cndmask_b32_e32 v16, v226, v17, vcc
	v_lshlrev_b32_e32 v25, 2, v16
	v_lshlrev_b32_e32 v16, 3, v184
	v_mov_b32_e32 v17, v179
	v_lshl_add_u64 v[16:17], s[4:5], 0, v[16:17]
	s_lshl_b64 s[4:5], s[96:97], 12
	s_add_u32 s4, s7, s4
	v_readlane_b32 s7, v254, 41
	s_addc_u32 s5, s7, s5
	v_readlane_b32 s14, v254, 22
	v_readlane_b32 s16, v254, 47
	v_readlane_b32 s66, v254, 53
	v_lshl_add_u64 v[18:19], s[4:5], 0, v[178:179]
	s_mov_b32 s4, s96
	v_readlane_b32 s15, v254, 23
	v_readlane_b32 s17, v254, 48
	v_readlane_b32 s57, v253, 31
	v_readlane_b32 s58, v253, 32
	v_readlane_b32 s59, v253, 33
	v_readlane_b32 s60, v253, 34
	v_readlane_b32 s61, v253, 35
	v_readlane_b32 s64, v253, 38
	v_readlane_b32 s65, v253, 39
	v_readlane_b32 s68, v253, 42
	v_readlane_b32 s69, v253, 43
	v_readlane_b32 s67, v254, 54
	s_cmp_eq_u32 s66, 0x800
	s_cbranch_scc0 .LBB0_197
.Lewi4_loop:
	v_lshl_add_u64 v[108:109], v[18:19], 0, s[16:17]
	v_lshl_add_u64 v[110:111], v[108:109], 0, s[16:17]
	v_lshl_add_u64 v[112:113], v[110:111], 0, s[16:17]
	global_load_dwordx4 v[26:29], v[18:19], off offset:-3072 nt
	global_load_dwordx4 v[30:33], v[18:19], off offset:-2048 nt
	global_load_dwordx4 v[34:37], v[18:19], off offset:-1024 nt
	global_load_dwordx4 v[38:41], v[18:19], off nt
	global_load_dwordx4 v[60:63], v[108:109], off offset:-3072 nt
	global_load_dwordx4 v[64:67], v[108:109], off offset:-2048 nt
	global_load_dwordx4 v[68:71], v[108:109], off offset:-1024 nt
	global_load_dwordx4 v[72:75], v[108:109], off nt
	global_load_dwordx4 v[76:79], v[110:111], off offset:-3072 nt
	global_load_dwordx4 v[80:83], v[110:111], off offset:-2048 nt
	global_load_dwordx4 v[84:87], v[110:111], off offset:-1024 nt
	global_load_dwordx4 v[88:91], v[110:111], off nt
	global_load_dwordx4 v[92:95], v[112:113], off offset:-3072 nt
	global_load_dwordx4 v[96:99], v[112:113], off offset:-2048 nt
	global_load_dwordx4 v[100:103], v[112:113], off offset:-1024 nt
	global_load_dwordx4 v[104:107], v[112:113], off nt
	v_lshl_add_u64 v[114:115], v[16:17], 0, s[14:15]
	v_lshl_add_u64 v[116:117], v[114:115], 0, s[14:15]
	v_lshl_add_u64 v[118:119], v[116:117], 0, s[14:15]
	s_waitcnt vmcnt(12)
	v_pk_mul_f32 v[42:43], v[28:29], v[28:29]
	v_pk_mul_f32 v[44:45], v[26:27], v[26:27]
	v_pk_mul_f32 v[46:47], v[32:33], v[32:33]
	v_pk_mul_f32 v[48:49], v[30:31], v[30:31]
	v_pk_mov_b32 v[54:55], v[44:45], v[42:43] op_sel:[1,0]
	v_mov_b32_e32 v45, v43
	v_pk_mov_b32 v[42:43], v[48:49], v[46:47] op_sel:[1,0]
	v_mov_b32_e32 v49, v47
	v_mul_f32_e32 v53, v38, v38
	v_mul_f32_e32 v50, v35, v35
	v_mul_f32_e32 v52, v37, v37
	v_pk_add_f32 v[44:45], v[54:55], v[44:45]
	v_pk_add_f32 v[42:43], v[42:43], v[48:49]
	v_mul_f32_e32 v56, v39, v39
	v_mul_f32_e32 v57, v40, v40
	v_mul_f32_e32 v58, v41, v41
	v_pk_fma_f32 v[46:47], v[34:35], v[34:35], v[50:51] op_sel_hi:[1,1,0]
	v_pk_fma_f32 v[50:51], v[36:37], v[36:37], v[52:53] op_sel_hi:[1,1,0]
	v_pk_add_f32 v[44:45], v[44:45], v[44:45] op_sel:[0,1] op_sel_hi:[1,0]
	v_pk_add_f32 v[42:43], v[42:43], v[42:43] op_sel:[0,1] op_sel_hi:[1,0]
	v_mov_b32_e32 v47, v57
	v_mov_b32_e32 v51, v58
	v_mov_b32_e32 v45, v53
	v_mov_b32_e32 v43, v56
	v_pk_add_f32 v[46:47], v[46:47], v[50:51]
	v_pk_add_f32 v[42:43], v[44:45], v[42:43]
	s_nop 0
	v_pk_add_f32 v[42:43], v[42:43], v[46:47]
	s_nop 0
	v_add_f32_e32 v42, v42, v43
	ds_bpermute_b32 v43, v20, v42
	s_waitcnt lgkmcnt(0)
	v_add_f32_e32 v42, v42, v43
	ds_bpermute_b32 v43, v21, v42
	s_waitcnt lgkmcnt(0)
	v_add_f32_e32 v42, v42, v43
	ds_bpermute_b32 v43, v22, v42
	s_waitcnt lgkmcnt(0)
	v_add_f32_e32 v42, v42, v43
	ds_bpermute_b32 v43, v23, v42
	s_waitcnt lgkmcnt(0)
	v_add_f32_e32 v42, v42, v43
	ds_bpermute_b32 v43, v24, v42
	s_waitcnt lgkmcnt(0)
	v_add_f32_e32 v42, v42, v43
	ds_bpermute_b32 v43, v25, v42
	s_waitcnt lgkmcnt(0)
; __device__ __forceinline__ unsigned pk2(float lo, float hi) { f32v2 v = {lo, hi}; bf16v2 r = __builtin_convertvector(v, bf16v2); return __builtin_bit_cast(unsigned, r); }
; __device__ __forceinline__ void ew_init(const float* x, const float* gain, bf16* H, int gw, int ngw, int lane) {
;     ...
;     for (int m = gw; m < NTOK; m += ngw) {
;         const f32x4* xr = (const f32x4*)(x + (size_t)m * DM) + lane; f32x4 v[4]; float s = 0.f;
; #pragma unroll
;         for (int j = 0; j < 4; ++j) { v[j] = __builtin_nontemporal_load(xr + 64 * j); s += (v[j].x * v[j].x + v[j].y * v[j].y) + (v[j].z * v[j].z + v[j].w * v[j].w); }
;         const float rstd = rsqrtf(wave_sum(s) * (1.f / DM) + RMS_EPS);
;         v2u* o = (v2u*)(H + (size_t)m * DM) + lane;
; #pragma unroll
;         for (int j = 0; j < 4; ++j) { v2u w; w.x = pk2(v[j].x * rstd * g[j].x, v[j].y * rstd * g[j].y); w.y = pk2(v[j].z * rstd * g[j].z, v[j].w * rstd * g[j].w); o[64 * j] = w; }
	v_add_f32_e32 v42, v42, v43
	v_fmamk_f32 v42, v42, 0x3a800000, v185
	v_mul_f32_e32 v43, 0x4b800000, v42
	v_cmp_gt_f32_e32 vcc, s3, v42
	s_nop 1
	v_cndmask_b32_e32 v42, v42, v43, vcc
	v_rsq_f32_e32 v42, v42
	s_nop 0
	v_mul_f32_e32 v43, 0x45800000, v42
	v_cndmask_b32_e32 v42, v42, v43, vcc
	v_pk_mul_f32 v[26:27], v[26:27], v[42:43] op_sel_hi:[1,0]
	v_pk_mul_f32 v[28:29], v[28:29], v[42:43] op_sel_hi:[1,0]
	v_pk_mul_f32 v[30:31], v[30:31], v[42:43] op_sel_hi:[1,0]
	v_pk_mul_f32 v[32:33], v[32:33], v[42:43] op_sel_hi:[1,0]
	v_pk_mul_f32 v[34:35], v[34:35], v[42:43] op_sel_hi:[1,0]
	v_pk_mul_f32 v[36:37], v[36:37], v[42:43] op_sel_hi:[1,0]
	v_pk_mul_f32 v[38:39], v[38:39], v[42:43] op_sel_hi:[1,0]
	v_pk_mul_f32 v[40:41], v[40:41], v[42:43] op_sel_hi:[1,0]
	v_pk_mul_f32 v[26:27], v[12:13], v[26:27]
	v_pk_mul_f32 v[28:29], v[14:15], v[28:29]
	v_pk_mul_f32 v[30:31], v[8:9], v[30:31]
	v_pk_mul_f32 v[32:33], v[10:11], v[32:33]
	v_pk_mul_f32 v[34:35], v[4:5], v[34:35]
	v_pk_mul_f32 v[36:37], v[6:7], v[36:37]
	v_pk_mul_f32 v[38:39], v[0:1], v[38:39]
	v_pk_mul_f32 v[40:41], v[2:3], v[40:41]
	v_cvt_pk_bf16_f32 v26, v26, v27
	v_cvt_pk_bf16_f32 v27, v28, v29
	v_cvt_pk_bf16_f32 v28, v30, v31
	v_cvt_pk_bf16_f32 v29, v32, v33
	v_cvt_pk_bf16_f32 v30, v34, v35
	v_cvt_pk_bf16_f32 v31, v36, v37
	v_cvt_pk_bf16_f32 v32, v38, v39
	v_cvt_pk_bf16_f32 v33, v40, v41
	global_store_dwordx2 v[16:17], v[26:27], off
	global_store_dwordx2 v[16:17], v[28:29], off offset:512
	global_store_dwordx2 v[16:17], v[30:31], off offset:1024
	global_store_dwordx2 v[16:17], v[32:33], off offset:1536
	s_waitcnt vmcnt(12)
	v_pk_mul_f32 v[42:43], v[62:63], v[62:63]
	v_pk_mul_f32 v[44:45], v[60:61], v[60:61]
	v_pk_mul_f32 v[46:47], v[66:67], v[66:67]
	v_pk_mul_f32 v[48:49], v[64:65], v[64:65]
	v_pk_mov_b32 v[54:55], v[44:45], v[42:43] op_sel:[1,0]
	v_mov_b32_e32 v45, v43
	v_pk_mov_b32 v[42:43], v[48:49], v[46:47] op_sel:[1,0]
	v_mov_b32_e32 v49, v47
	v_mul_f32_e32 v53, v72, v72
	v_mul_f32_e32 v50, v69, v69
	v_mul_f32_e32 v52, v71, v71
	v_pk_add_f32 v[44:45], v[54:55], v[44:45]
	v_pk_add_f32 v[42:43], v[42:43], v[48:49]
	v_mul_f32_e32 v56, v73, v73
	v_mul_f32_e32 v57, v74, v74
	v_mul_f32_e32 v58, v75, v75
	v_pk_fma_f32 v[46:47], v[68:69], v[68:69], v[50:51] op_sel_hi:[1,1,0]
	v_pk_fma_f32 v[50:51], v[70:71], v[70:71], v[52:53] op_sel_hi:[1,1,0]
	v_pk_add_f32 v[44:45], v[44:45], v[44:45] op_sel:[0,1] op_sel_hi:[1,0]
	v_pk_add_f32 v[42:43], v[42:43], v[42:43] op_sel:[0,1] op_sel_hi:[1,0]
	v_mov_b32_e32 v47, v57
	v_mov_b32_e32 v51, v58
	v_mov_b32_e32 v45, v53
	v_mov_b32_e32 v43, v56
	v_pk_add_f32 v[46:47], v[46:47], v[50:51]
	v_pk_add_f32 v[42:43], v[44:45], v[42:43]
	s_nop 0
	v_pk_add_f32 v[42:43], v[42:43], v[46:47]
	s_nop 0
	v_add_f32_e32 v42, v42, v43
	ds_bpermute_b32 v43, v20, v42
	s_waitcnt lgkmcnt(0)
	v_add_f32_e32 v42, v42, v43
	ds_bpermute_b32 v43, v21, v42
	s_waitcnt lgkmcnt(0)
	v_add_f32_e32 v42, v42, v43
	ds_bpermute_b32 v43, v22, v42
	s_waitcnt lgkmcnt(0)
	v_add_f32_e32 v42, v42, v43
	ds_bpermute_b32 v43, v23, v42
	s_waitcnt lgkmcnt(0)
	v_add_f32_e32 v42, v42, v43
	ds_bpermute_b32 v43, v24, v42
	s_waitcnt lgkmcnt(0)
	v_add_f32_e32 v42, v42, v43
	ds_bpermute_b32 v43, v25, v42
	s_waitcnt lgkmcnt(0)
	v_add_f32_e32 v42, v42, v43
	v_fmamk_f32 v42, v42, 0x3a800000, v185
	v_mul_f32_e32 v43, 0x4b800000, v42
	v_cmp_gt_f32_e32 vcc, s3, v42
	s_nop 1
	v_cndmask_b32_e32 v42, v42, v43, vcc
	v_rsq_f32_e32 v42, v42
	s_nop 0
	v_mul_f32_e32 v43, 0x45800000, v42
	v_cndmask_b32_e32 v42, v42, v43, vcc
	v_pk_mul_f32 v[60:61], v[60:61], v[42:43] op_sel_hi:[1,0]
	v_pk_mul_f32 v[62:63], v[62:63], v[42:43] op_sel_hi:[1,0]
	v_pk_mul_f32 v[64:65], v[64:65], v[42:43] op_sel_hi:[1,0]
	v_pk_mul_f32 v[66:67], v[66:67], v[42:43] op_sel_hi:[1,0]
	v_pk_mul_f32 v[68:69], v[68:69], v[42:43] op_sel_hi:[1,0]
	v_pk_mul_f32 v[70:71], v[70:71], v[42:43] op_sel_hi:[1,0]
	v_pk_mul_f32 v[72:73], v[72:73], v[42:43] op_sel_hi:[1,0]
	v_pk_mul_f32 v[74:75], v[74:75], v[42:43] op_sel_hi:[1,0]
	v_pk_mul_f32 v[60:61], v[12:13], v[60:61]
	v_pk_mul_f32 v[62:63], v[14:15], v[62:63]
	v_pk_mul_f32 v[64:65], v[8:9], v[64:65]
	v_pk_mul_f32 v[66:67], v[10:11], v[66:67]
	v_pk_mul_f32 v[68:69], v[4:5], v[68:69]
	v_pk_mul_f32 v[70:71], v[6:7], v[70:71]
	v_pk_mul_f32 v[72:73], v[0:1], v[72:73]
	v_pk_mul_f32 v[74:75], v[2:3], v[74:75]
	v_cvt_pk_bf16_f32 v60, v60, v61
	v_cvt_pk_bf16_f32 v61, v62, v63
	v_cvt_pk_bf16_f32 v62, v64, v65
	v_cvt_pk_bf16_f32 v63, v66, v67
	v_cvt_pk_bf16_f32 v64, v68, v69
	v_cvt_pk_bf16_f32 v65, v70, v71
	v_cvt_pk_bf16_f32 v66, v72, v73
	v_cvt_pk_bf16_f32 v67, v74, v75
	global_store_dwordx2 v[114:115], v[60:61], off
	global_store_dwordx2 v[114:115], v[62:63], off offset:512
	global_store_dwordx2 v[114:115], v[64:65], off offset:1024
	global_store_dwordx2 v[114:115], v[66:67], off offset:1536
	s_waitcnt vmcnt(12)
	v_pk_mul_f32 v[42:43], v[78:79], v[78:79]
	v_pk_mul_f32 v[44:45], v[76:77], v[76:77]
	v_pk_mul_f32 v[46:47], v[82:83], v[82:83]
	v_pk_mul_f32 v[48:49], v[80:81], v[80:81]
	v_pk_mov_b32 v[54:55], v[44:45], v[42:43] op_sel:[1,0]
	v_mov_b32_e32 v45, v43
	v_pk_mov_b32 v[42:43], v[48:49], v[46:47] op_sel:[1,0]
	v_mov_b32_e32 v49, v47
	v_mul_f32_e32 v53, v88, v88
	v_mul_f32_e32 v50, v85, v85
	v_mul_f32_e32 v52, v87, v87
	v_pk_add_f32 v[44:45], v[54:55], v[44:45]
	v_pk_add_f32 v[42:43], v[42:43], v[48:49]
	v_mul_f32_e32 v56, v89, v89
	v_mul_f32_e32 v57, v90, v90
	v_mul_f32_e32 v58, v91, v91
	v_pk_fma_f32 v[46:47], v[84:85], v[84:85], v[50:51] op_sel_hi:[1,1,0]
	v_pk_fma_f32 v[50:51], v[86:87], v[86:87], v[52:53] op_sel_hi:[1,1,0]
	v_pk_add_f32 v[44:45], v[44:45], v[44:45] op_sel:[0,1] op_sel_hi:[1,0]
	v_pk_add_f32 v[42:43], v[42:43], v[42:43] op_sel:[0,1] op_sel_hi:[1,0]
	v_mov_b32_e32 v47, v57
	v_mov_b32_e32 v51, v58
	v_mov_b32_e32 v45, v53
	v_mov_b32_e32 v43, v56
	v_pk_add_f32 v[46:47], v[46:47], v[50:51]
	v_pk_add_f32 v[42:43], v[44:45], v[42:43]
	s_nop 0
	v_pk_add_f32 v[42:43], v[42:43], v[46:47]
	s_nop 0
	v_add_f32_e32 v42, v42, v43
	ds_bpermute_b32 v43, v20, v42
	s_waitcnt lgkmcnt(0)
; __device__ __forceinline__ unsigned pk2(float lo, float hi) { f32v2 v = {lo, hi}; bf16v2 r = __builtin_convertvector(v, bf16v2); return __builtin_bit_cast(unsigned, r); }
; __device__ __forceinline__ void ew_init(const float* x, const float* gain, bf16* H, int gw, int ngw, int lane) {
;     ...
;     for (int m = gw; m < NTOK; m += ngw) {
;         const f32x4* xr = (const f32x4*)(x + (size_t)m * DM) + lane; f32x4 v[4]; float s = 0.f;
; #pragma unroll
;         for (int j = 0; j < 4; ++j) { v[j] = __builtin_nontemporal_load(xr + 64 * j); s += (v[j].x * v[j].x + v[j].y * v[j].y) + (v[j].z * v[j].z + v[j].w * v[j].w); }
;         const float rstd = rsqrtf(wave_sum(s) * (1.f / DM) + RMS_EPS);
;         v2u* o = (v2u*)(H + (size_t)m * DM) + lane;
; #pragma unroll
;         for (int j = 0; j < 4; ++j) { v2u w; w.x = pk2(v[j].x * rstd * g[j].x, v[j].y * rstd * g[j].y); w.y = pk2(v[j].z * rstd * g[j].z, v[j].w * rstd * g[j].w); o[64 * j] = w; }
;     }
	v_add_f32_e32 v42, v42, v43
	ds_bpermute_b32 v43, v21, v42
	s_waitcnt lgkmcnt(0)
	v_add_f32_e32 v42, v42, v43
	ds_bpermute_b32 v43, v22, v42
	s_waitcnt lgkmcnt(0)
	v_add_f32_e32 v42, v42, v43
	ds_bpermute_b32 v43, v23, v42
	s_waitcnt lgkmcnt(0)
	v_add_f32_e32 v42, v42, v43
	ds_bpermute_b32 v43, v24, v42
	s_waitcnt lgkmcnt(0)
	v_add_f32_e32 v42, v42, v43
	ds_bpermute_b32 v43, v25, v42
	s_waitcnt lgkmcnt(0)
	v_add_f32_e32 v42, v42, v43
	v_fmamk_f32 v42, v42, 0x3a800000, v185
	v_mul_f32_e32 v43, 0x4b800000, v42
	v_cmp_gt_f32_e32 vcc, s3, v42
	s_nop 1
	v_cndmask_b32_e32 v42, v42, v43, vcc
	v_rsq_f32_e32 v42, v42
	s_nop 0
	v_mul_f32_e32 v43, 0x45800000, v42
	v_cndmask_b32_e32 v42, v42, v43, vcc
	v_pk_mul_f32 v[76:77], v[76:77], v[42:43] op_sel_hi:[1,0]
	v_pk_mul_f32 v[78:79], v[78:79], v[42:43] op_sel_hi:[1,0]
	v_pk_mul_f32 v[80:81], v[80:81], v[42:43] op_sel_hi:[1,0]
	v_pk_mul_f32 v[82:83], v[82:83], v[42:43] op_sel_hi:[1,0]
	v_pk_mul_f32 v[84:85], v[84:85], v[42:43] op_sel_hi:[1,0]
	v_pk_mul_f32 v[86:87], v[86:87], v[42:43] op_sel_hi:[1,0]
	v_pk_mul_f32 v[88:89], v[88:89], v[42:43] op_sel_hi:[1,0]
	v_pk_mul_f32 v[90:91], v[90:91], v[42:43] op_sel_hi:[1,0]
	v_pk_mul_f32 v[76:77], v[12:13], v[76:77]
	v_pk_mul_f32 v[78:79], v[14:15], v[78:79]
	v_pk_mul_f32 v[80:81], v[8:9], v[80:81]
	v_pk_mul_f32 v[82:83], v[10:11], v[82:83]
	v_pk_mul_f32 v[84:85], v[4:5], v[84:85]
	v_pk_mul_f32 v[86:87], v[6:7], v[86:87]
	v_pk_mul_f32 v[88:89], v[0:1], v[88:89]
	v_pk_mul_f32 v[90:91], v[2:3], v[90:91]
	v_cvt_pk_bf16_f32 v76, v76, v77
	v_cvt_pk_bf16_f32 v77, v78, v79
	v_cvt_pk_bf16_f32 v78, v80, v81
	v_cvt_pk_bf16_f32 v79, v82, v83
	v_cvt_pk_bf16_f32 v80, v84, v85
	v_cvt_pk_bf16_f32 v81, v86, v87
	v_cvt_pk_bf16_f32 v82, v88, v89
	v_cvt_pk_bf16_f32 v83, v90, v91
	global_store_dwordx2 v[116:117], v[76:77], off
	global_store_dwordx2 v[116:117], v[78:79], off offset:512
	global_store_dwordx2 v[116:117], v[80:81], off offset:1024
	global_store_dwordx2 v[116:117], v[82:83], off offset:1536
	s_waitcnt vmcnt(12)
	v_pk_mul_f32 v[42:43], v[94:95], v[94:95]
	v_pk_mul_f32 v[44:45], v[92:93], v[92:93]
	v_pk_mul_f32 v[46:47], v[98:99], v[98:99]
	v_pk_mul_f32 v[48:49], v[96:97], v[96:97]
	v_pk_mov_b32 v[54:55], v[44:45], v[42:43] op_sel:[1,0]
	v_mov_b32_e32 v45, v43
	v_pk_mov_b32 v[42:43], v[48:49], v[46:47] op_sel:[1,0]
	v_mov_b32_e32 v49, v47
	v_mul_f32_e32 v53, v104, v104
	v_mul_f32_e32 v50, v101, v101
	v_mul_f32_e32 v52, v103, v103
	v_pk_add_f32 v[44:45], v[54:55], v[44:45]
	v_pk_add_f32 v[42:43], v[42:43], v[48:49]
	v_mul_f32_e32 v56, v105, v105
	v_mul_f32_e32 v57, v106, v106
	v_mul_f32_e32 v58, v107, v107
	v_pk_fma_f32 v[46:47], v[100:101], v[100:101], v[50:51] op_sel_hi:[1,1,0]
	v_pk_fma_f32 v[50:51], v[102:103], v[102:103], v[52:53] op_sel_hi:[1,1,0]
	v_pk_add_f32 v[44:45], v[44:45], v[44:45] op_sel:[0,1] op_sel_hi:[1,0]
	v_pk_add_f32 v[42:43], v[42:43], v[42:43] op_sel:[0,1] op_sel_hi:[1,0]
	v_mov_b32_e32 v47, v57
	v_mov_b32_e32 v51, v58
	v_mov_b32_e32 v45, v53
	v_mov_b32_e32 v43, v56
	v_pk_add_f32 v[46:47], v[46:47], v[50:51]
	v_pk_add_f32 v[42:43], v[44:45], v[42:43]
	s_nop 0
	v_pk_add_f32 v[42:43], v[42:43], v[46:47]
	s_nop 0
	v_add_f32_e32 v42, v42, v43
	ds_bpermute_b32 v43, v20, v42
	s_waitcnt lgkmcnt(0)
	v_add_f32_e32 v42, v42, v43
	ds_bpermute_b32 v43, v21, v42
	s_waitcnt lgkmcnt(0)
	v_add_f32_e32 v42, v42, v43
	ds_bpermute_b32 v43, v22, v42
	s_waitcnt lgkmcnt(0)
	v_add_f32_e32 v42, v42, v43
	ds_bpermute_b32 v43, v23, v42
	s_waitcnt lgkmcnt(0)
	v_add_f32_e32 v42, v42, v43
	ds_bpermute_b32 v43, v24, v42
	s_waitcnt lgkmcnt(0)
	v_add_f32_e32 v42, v42, v43
	ds_bpermute_b32 v43, v25, v42
	s_waitcnt lgkmcnt(0)
	v_add_f32_e32 v42, v42, v43
	v_fmamk_f32 v42, v42, 0x3a800000, v185
	v_mul_f32_e32 v43, 0x4b800000, v42
	v_cmp_gt_f32_e32 vcc, s3, v42
	s_nop 1
	v_cndmask_b32_e32 v42, v42, v43, vcc
	v_rsq_f32_e32 v42, v42
	s_nop 0
	v_mul_f32_e32 v43, 0x45800000, v42
	v_cndmask_b32_e32 v42, v42, v43, vcc
	v_pk_mul_f32 v[92:93], v[92:93], v[42:43] op_sel_hi:[1,0]
	v_pk_mul_f32 v[94:95], v[94:95], v[42:43] op_sel_hi:[1,0]
	v_pk_mul_f32 v[96:97], v[96:97], v[42:43] op_sel_hi:[1,0]
	v_pk_mul_f32 v[98:99], v[98:99], v[42:43] op_sel_hi:[1,0]
	v_pk_mul_f32 v[100:101], v[100:101], v[42:43] op_sel_hi:[1,0]
	v_pk_mul_f32 v[102:103], v[102:103], v[42:43] op_sel_hi:[1,0]
	v_pk_mul_f32 v[104:105], v[104:105], v[42:43] op_sel_hi:[1,0]
	v_pk_mul_f32 v[106:107], v[106:107], v[42:43] op_sel_hi:[1,0]
	v_pk_mul_f32 v[92:93], v[12:13], v[92:93]
	v_pk_mul_f32 v[94:95], v[14:15], v[94:95]
	v_pk_mul_f32 v[96:97], v[8:9], v[96:97]
	v_pk_mul_f32 v[98:99], v[10:11], v[98:99]
	v_pk_mul_f32 v[100:101], v[4:5], v[100:101]
	v_pk_mul_f32 v[102:103], v[6:7], v[102:103]
	v_pk_mul_f32 v[104:105], v[0:1], v[104:105]
	v_pk_mul_f32 v[106:107], v[2:3], v[106:107]
	v_cvt_pk_bf16_f32 v92, v92, v93
	v_cvt_pk_bf16_f32 v93, v94, v95
	v_cvt_pk_bf16_f32 v94, v96, v97
	v_cvt_pk_bf16_f32 v95, v98, v99
	v_cvt_pk_bf16_f32 v96, v100, v101
	v_cvt_pk_bf16_f32 v97, v102, v103
	v_cvt_pk_bf16_f32 v98, v104, v105
	v_cvt_pk_bf16_f32 v99, v106, v107
	global_store_dwordx2 v[118:119], v[92:93], off
	global_store_dwordx2 v[118:119], v[94:95], off offset:512
	global_store_dwordx2 v[118:119], v[96:97], off offset:1024
	global_store_dwordx2 v[118:119], v[98:99], off offset:1536
	v_lshl_add_u64 v[18:19], v[112:113], 0, s[16:17]
	v_lshl_add_u64 v[16:17], v[118:119], 0, s[14:15]
	s_addk_i32 s4, 0x2000
	s_cmpk_gt_i32 s4, 0x7fff
	s_cbranch_scc0 .Lewi4_loop
	s_branch .Lewi4_done

; __global__ void __launch_bounds__(NTHREADS, 2) fwd_megakernel(Args A) {
;     ...
;             if (it == 0) ew_init(A.in[0], A.in[11], H, gw, ngw, lane);
;             else ew_post(Y, xres, xres, A.in[14] + (size_t)l * DM, l + 1 < DEPTH ? A.in[11] + (size_t)(l + 1) * DM : nullptr, H, gw, ngw, lane);
.Lewi4_done:
	v_readlane_b32 s68, v254, 55
	v_readlane_b32 s42, v254, 62
	v_readlane_b32 s46, v255, 0
	v_readlane_b32 s60, v255, 2
	s_mov_b32 s97, s6
	v_readlane_b32 s69, v254, 56
	v_readlane_b32 s63, v254, 59
	v_readlane_b32 s43, v254, 63
	v_readlane_b32 s47, v255, 1
	v_readlane_b32 s61, v255, 3
